# v16: v8 + GEMM K-loop LDS-DMA loads in SGPR-base form (192 sites) with M0 / VALU-SGPR hazard pads; removes per-load 64-bit VALU address add
# speedup vs baseline: 1.0115x; 1.0000x over previous
; #define PG8_WAIT_V(n) asm volatile("s_waitcnt vmcnt(" #n ")" ::: "memory")
; #define PG8_BAR __builtin_amdgcn_s_barrier()
;     ...
;     const int aoff = lds_byte(wr * 64 + fr, fq * 8), boff = lds_byte(wc * 32 + fr, fq * 8);
;     ...
;         PG8_STAGE(PG8_SB(0, 0), cB, voffB); PG8_STAGE(PG8_SB(0, 1), cB + hstep, voffB); PG8_STAGE(PG8_SA(0, 0), cA, voffA); PG8_STAGE(PG8_SA(0, 1), cA + hstepA, voffA);
;         if (wr == 1) PG8_BAR;
;         PG8_WAIT_V(2); PG8_BAR;
;         PG8_STAGE(PG8_SB(1, 0), cB + kstep, voffB); PG8_STAGE(PG8_SA(1, 0), cA + kstep, voffA); PG8_STAGE(PG8_SB(1, 1), cB + hstep + kstep, voffB);
;         PG8_WAIT_V(6); PG8_BAR;
.LBB0_311:
	v_readlane_b32 s12, v254, 11
	v_readlane_b32 s20, v254, 13
	v_readlane_b32 s13, v254, 12
	v_readlane_b32 s21, v254, 14
	s_and_b32 s5, s5, 3
	s_and_b32 s85, s93, 0xffff
	s_and_b32 s9, s13, 0xffff
	s_and_b32 s13, s21, 0xffff
	s_ashr_i32 s45, s88, 31
	s_ashr_i32 s46, s90, 31
	s_lshl_b32 s47, s8, 6
	s_lshl_b32 s7, s8, 13
	s_lshl_b32 s48, s5, 5
	s_lshl_b32 s16, s5, 12
	s_add_u32 s10, s30, 0x80
	s_addc_u32 s11, s31, 0
	s_add_i32 m0, s29, 0x18000
	s_waitcnt vmcnt(2)
	s_barrier
	global_load_lds_dwordx4 v144, s[10:11]
	s_add_i32 m0, s29, 0x1a000
	v_lshl_add_u64 v[2:3], s[10:11], 0, v[148:149]
	s_add_u32 s10, s14, 0x80
	s_addc_u32 s11, s15, 0
	s_add_i32 s49, s29, 0x8000
	global_load_lds_dwordx4 v[2:3], off
	s_mov_b32 m0, s49
	s_add_i32 s50, s29, 0xa000
	global_load_lds_dwordx4 v252, s[10:11]
	v_lshl_add_u64 v[2:3], s[10:11], 0, v[146:147]
	s_add_u32 s10, s30, 0x80080
	s_mov_b32 m0, s50
	s_addc_u32 s11, s31, 0
	global_load_lds_dwordx4 v[2:3], off
	s_add_i32 m0, s29, 0x1c000
	s_nop 0
	global_load_lds_dwordx4 v144, s[10:11]
	s_add_i32 m0, s29, 0x1e000
	v_and_b32_e32 v1, 48, v0
	global_load_lds_dwordx4 v148, s[10:11]
	v_lshlrev_b32_e32 v2, 6, v0
	s_movk_i32 s17, 0x3c0
	v_lshlrev_b32_e32 v0, 2, v0
	v_and_or_b32 v1, v2, s17, v1
	v_and_b32_e32 v0, 32, v0
	s_waitcnt vmcnt(6)
	s_cmpk_lt_u32 s4, 0x100
	s_mov_b32 s87, 0x20000
	v_bitop3_b32 v2, v1, s7, v0 bitop3:0xde
	v_bitop3_b32 v154, s16, v1, v0 bitop3:0xf6
	s_cselect_b64 s[16:17], -1, 0
	s_add_i32 s53, 0, 0x10000
	s_add_i32 s54, 0, 0x14000
	s_brev_b32 s86, 36
	s_mov_b32 s8, s12
	s_mov_b32 s10, 0x400000
	s_mov_b32 s11, s87
	s_mov_b32 s12, s20
	s_lshl_b32 s51, s5, 6
	s_movk_i32 s52, 0x241
	v_add_u32_e32 v155, s53, v154
	v_add_u32_e32 v156, s54, v154
	v_add_u32_e32 v157, 0, v2
	v_mov_b32_e32 v158, 0x7f7f7f7f
	s_mov_b32 s18, 0x3c800000
	v_mov_b32_e32 v159, 0x1fcf
	s_barrier
	s_branch .LBB0_314

; #define PG8_WAIT_V(n) asm volatile("s_waitcnt vmcnt(" #n ")" ::: "memory")
; #define PG8_BAR __builtin_amdgcn_s_barrier()
;     ...
;     const int aoff = lds_byte(wr * 64 + fr, fq * 8), boff = lds_byte(wc * 32 + fr, fq * 8);
;     ...
;         PG8_STAGE(PG8_SB(0, 0), cB, voffB); PG8_STAGE(PG8_SB(0, 1), cB + hstep, voffB); PG8_STAGE(PG8_SA(0, 0), cA, voffA); PG8_STAGE(PG8_SA(0, 1), cA + hstepA, voffA);
;         if (wr == 1) PG8_BAR;
;         PG8_WAIT_V(2); PG8_BAR;
;         PG8_STAGE(PG8_SB(1, 0), cB + kstep, voffB); PG8_STAGE(PG8_SA(1, 0), cA + kstep, voffA); PG8_STAGE(PG8_SB(1, 1), cB + hstep + kstep, voffB);
;         PG8_WAIT_V(6); PG8_BAR;
.LBB0_532:
	s_lshl_b32 s6, s6, 5
	s_and_b32 s52, s6, 0x60
	s_and_b32 s13, s35, 0xffff
	s_ashr_i32 s50, s88, 31
	s_waitcnt lgkmcnt(0)
	s_and_b32 s9, s9, 0xffff
	s_lshl_b32 s51, s7, 6
	s_lshl_b32 s16, s7, 13
	s_lshl_b32 s18, s52, 7
	s_add_u32 s6, s30, 0x80
	s_addc_u32 s7, s31, 0
	s_add_i32 m0, s45, 0x18000
	s_waitcnt vmcnt(2)
	s_barrier
	global_load_lds_dwordx4 v128, s[6:7]
	s_add_i32 m0, s45, 0x1a000
	v_lshl_add_u64 v[2:3], s[6:7], 0, v[130:131]
	s_add_u32 s6, s28, 0x80
	s_addc_u32 s7, s29, 0
	s_add_i32 s53, s45, 0x8000
	global_load_lds_dwordx4 v[2:3], off
	s_mov_b32 m0, s53
	s_add_i32 s54, s45, 0xa000
	global_load_lds_dwordx4 v128, s[6:7]
	v_lshl_add_u64 v[2:3], s[6:7], 0, v[130:131]
	s_add_u32 s6, s30, 0x40080
	s_mov_b32 m0, s54
	s_addc_u32 s7, s31, 0
	global_load_lds_dwordx4 v[2:3], off
	s_add_i32 m0, s45, 0x1c000
	s_nop 0
	global_load_lds_dwordx4 v128, s[6:7]
	s_add_i32 m0, s45, 0x1e000
	s_sext_i32_i8 s15, s4
	global_load_lds_dwordx4 v130, s[6:7]
	v_and_b32_e32 v1, 48, v0
	v_lshlrev_b32_e32 v2, 6, v0
	s_movk_i32 s4, 0x3c0
	v_lshlrev_b32_e32 v0, 2, v0
	v_and_or_b32 v1, v2, s4, v1
	v_and_b32_e32 v0, 32, v0
	s_waitcnt vmcnt(6)
	s_cmpk_lt_u32 s5, 0x100
	v_bitop3_b32 v2, v1, s16, v0 bitop3:0xde
	v_bitop3_b32 v136, s18, v1, v0 bitop3:0xf6
	s_cselect_b64 s[6:7], -1, 0
	s_add_i32 s55, 0, 0x10000
	s_add_i32 s56, 0, 0x14000
	s_mov_b32 s12, s34
	s_mov_b32 s11, 0x20000
	s_brev_b32 s10, 8
	v_mov_b64_e32 v[132:133], 0x400
	v_mov_b64_e32 v[134:135], 0x3ff
	v_add_u32_e32 v137, s55, v136
	v_add_u32_e32 v138, s56, v136
	v_add_u32_e32 v139, 0, v2
	v_mov_b32_e32 v140, 0x7f7f7f7f
	s_mov_b32 s16, 0x3fb504f3
	s_mov_b32 s18, 0x3a800000
	s_barrier
	s_branch .LBB0_535

; #define PG8_WAIT_V(n) asm volatile("s_waitcnt vmcnt(" #n ")" ::: "memory")
; #define PG8_BAR __builtin_amdgcn_s_barrier()
;     ...
;     const int aoff = lds_byte(wr * 64 + fr, fq * 8), boff = lds_byte(wc * 32 + fr, fq * 8);
;     ...
;         PG8_STAGE(PG8_SB(0, 0), cB, voffB); PG8_STAGE(PG8_SB(0, 1), cB + hstep, voffB); PG8_STAGE(PG8_SA(0, 0), cA, voffA); PG8_STAGE(PG8_SA(0, 1), cA + hstepA, voffA);
;         if (wr == 1) PG8_BAR;
;         PG8_WAIT_V(2); PG8_BAR;
;         PG8_STAGE(PG8_SB(1, 0), cB + kstep, voffB); PG8_STAGE(PG8_SA(1, 0), cA + kstep, voffA); PG8_STAGE(PG8_SB(1, 1), cB + hstep + kstep, voffB);
;         PG8_WAIT_V(6); PG8_BAR;
.LBB0_664:
	s_lshl_b32 s6, s6, 5
	s_and_b32 s42, s6, 0x60
	s_ashr_i32 s40, s88, 31
	s_lshl_b32 s41, s7, 6
	s_lshl_b32 s8, s7, 13
	s_lshl_b32 s9, s42, 7
	s_add_u32 s6, s20, 0x80
	s_addc_u32 s7, s21, 0
	s_add_i32 m0, s17, 0x18000
	s_waitcnt vmcnt(2)
	s_barrier
	global_load_lds_dwordx4 v128, s[6:7]
	s_add_i32 m0, s17, 0x1a000
	v_lshl_add_u64 v[2:3], s[6:7], 0, v[130:131]
	s_add_u32 s6, s18, 0x80
	s_addc_u32 s7, s19, 0
	s_add_i32 s43, s17, 0x8000
	global_load_lds_dwordx4 v[2:3], off
	s_mov_b32 m0, s43
	s_add_i32 s44, s17, 0xa000
	global_load_lds_dwordx4 v134, s[6:7]
	v_lshl_add_u64 v[2:3], s[6:7], 0, v[132:133]
	s_add_u32 s6, s20, 0x100080
	s_mov_b32 m0, s44
	s_addc_u32 s7, s21, 0
	global_load_lds_dwordx4 v[2:3], off
	s_add_i32 m0, s17, 0x1c000
	s_nop 0
	global_load_lds_dwordx4 v128, s[6:7]
	s_add_i32 m0, s17, 0x1e000
	s_sext_i32_i16 s48, s4
	global_load_lds_dwordx4 v130, s[6:7]
	v_and_b32_e32 v1, 48, v0
	v_lshlrev_b32_e32 v2, 6, v0
	s_movk_i32 s4, 0x3c0
	v_lshlrev_b32_e32 v0, 2, v0
	v_and_or_b32 v1, v2, s4, v1
	v_and_b32_e32 v0, 32, v0
	s_waitcnt vmcnt(6)
	s_cmpk_lt_u32 s5, 0x100
	v_bitop3_b32 v2, v1, s8, v0 bitop3:0xde
	v_bitop3_b32 v140, s9, v1, v0 bitop3:0xf6
	s_cselect_b64 s[6:7], -1, 0
	s_add_i32 s45, 0, 0x10000
	s_add_i32 s46, 0, 0x14000
	v_mov_b64_e32 v[136:137], 0x1580
	v_mov_b64_e32 v[138:139], 0x157f
	v_add_u32_e32 v141, s45, v140
	v_add_u32_e32 v142, s46, v140
	v_add_u32_e32 v143, 0, v2
	s_movk_i32 s47, 0x5600
	s_barrier
	s_branch .LBB0_667

; #define PG8_WAIT_V(n) asm volatile("s_waitcnt vmcnt(" #n ")" ::: "memory")
; #define PG8_BAR __builtin_amdgcn_s_barrier()
;     ...
;     const int aoff = lds_byte(wr * 64 + fr, fq * 8), boff = lds_byte(wc * 32 + fr, fq * 8);
;     ...
;         PG8_STAGE(PG8_SB(0, 0), cB, voffB); PG8_STAGE(PG8_SB(0, 1), cB + hstep, voffB); PG8_STAGE(PG8_SA(0, 0), cA, voffA); PG8_STAGE(PG8_SA(0, 1), cA + hstepA, voffA);
;         if (wr == 1) PG8_BAR;
;         PG8_WAIT_V(2); PG8_BAR;
;         PG8_STAGE(PG8_SB(1, 0), cB + kstep, voffB); PG8_STAGE(PG8_SA(1, 0), cA + kstep, voffA); PG8_STAGE(PG8_SB(1, 1), cB + hstep + kstep, voffB);
;         PG8_WAIT_V(6); PG8_BAR;
.LBB0_779:
	s_and_b32 s6, s6, 3
	s_and_b32 s17, s58, 0xffff
	s_and_b32 s9, s35, 0xffff
	s_ashr_i32 s41, s88, 31
	s_lshl_b32 s42, s5, 6
	s_lshl_b32 s5, s5, 13
	s_lshl_b32 s14, s6, 12
	s_add_u32 s12, s22, 0x80
	s_addc_u32 s13, s23, 0
	s_add_i32 m0, s36, 0x18000
	s_waitcnt vmcnt(2)
	s_barrier
	global_load_lds_dwordx4 v128, s[12:13]
	s_add_i32 m0, s36, 0x1a000
	v_lshl_add_u64 v[2:3], s[12:13], 0, v[130:131]
	s_add_u32 s12, s10, 0x80
	s_addc_u32 s13, s11, 0
	s_add_i32 s43, s36, 0x8000
	global_load_lds_dwordx4 v[2:3], off
	s_mov_b32 m0, s43
	s_add_i32 s44, s36, 0xa000
	global_load_lds_dwordx4 v128, s[12:13]
	v_lshl_add_u64 v[2:3], s[12:13], 0, v[130:131]
	s_add_u32 s12, s22, 0x2b0080
	s_mov_b32 m0, s44
	s_addc_u32 s13, s23, 0
	global_load_lds_dwordx4 v[2:3], off
	s_add_i32 m0, s36, 0x1c000
	s_nop 0
	global_load_lds_dwordx4 v128, s[12:13]
	s_add_i32 m0, s36, 0x1e000
	s_sext_i32_i8 s51, s7
	global_load_lds_dwordx4 v130, s[12:13]
	v_and_b32_e32 v1, 48, v0
	v_lshlrev_b32_e32 v2, 6, v0
	s_movk_i32 s7, 0x3c0
	v_lshlrev_b32_e32 v0, 2, v0
	v_and_or_b32 v1, v2, s7, v1
	v_and_b32_e32 v0, 32, v0
	s_waitcnt vmcnt(6)
	s_cmpk_lt_u32 s4, 0x100
	v_bitop3_b32 v2, v1, s5, v0 bitop3:0xde
	v_bitop3_b32 v136, s14, v1, v0 bitop3:0xf6
	s_cselect_b64 s[12:13], -1, 0
	s_add_i32 s46, 0, 0x10000
	s_add_i32 s47, 0, 0x14000
	s_mov_b32 s19, 0x20000
	s_brev_b32 s18, 8
	s_mov_b32 s8, s34
	s_lshl_b32 s45, s6, 6
	v_mov_b64_e32 v[132:133], 0x400
	v_mov_b64_e32 v[134:135], 0x3ff
	v_add_u32_e32 v137, s46, v136
	v_add_u32_e32 v138, s47, v136
	v_add_u32_e32 v139, 0, v2
	s_mov_b32 s14, 0x3fb504f3
	s_barrier
	s_branch .LBB0_782

; #define PG8_WAIT_V(n) asm volatile("s_waitcnt vmcnt(" #n ")" ::: "memory")
; #define PG8_BAR __builtin_amdgcn_s_barrier()
;     ...
;     const int aoff = lds_byte(wr * 64 + fr, fq * 8), boff = lds_byte(wc * 32 + fr, fq * 8);
;     ...
;         PG8_STAGE(PG8_SB(0, 0), cB, voffB); PG8_STAGE(PG8_SB(0, 1), cB + hstep, voffB); PG8_STAGE(PG8_SA(0, 0), cA, voffA); PG8_STAGE(PG8_SA(0, 1), cA + hstepA, voffA);
;         if (wr == 1) PG8_BAR;
;         PG8_WAIT_V(2); PG8_BAR;
;         PG8_STAGE(PG8_SB(1, 0), cB + kstep, voffB); PG8_STAGE(PG8_SA(1, 0), cA + kstep, voffA); PG8_STAGE(PG8_SB(1, 1), cB + hstep + kstep, voffB);
;         PG8_WAIT_V(6); PG8_BAR;
.LBB0_1194:
	v_readlane_b32 s28, v254, 11
	v_readlane_b32 s30, v254, 13
	v_readlane_b32 s29, v254, 12
	v_readlane_b32 s31, v254, 14
	s_and_b32 s5, s5, 3
	s_and_b32 s85, s93, 0xffff
	s_and_b32 s21, s59, 0xffff
	s_and_b32 s25, s60, 0xffff
	s_and_b32 s13, s29, 0xffff
	s_and_b32 s29, s31, 0xffff
	s_lshl_b32 s66, s12, 6
	s_lshl_b32 s7, s12, 13
	s_lshl_b32 s67, s5, 5
	s_lshl_b32 s9, s5, 12
	s_waitcnt lgkmcnt(0)
	s_add_u32 s14, s26, 0x80
	s_addc_u32 s15, s27, 0
	s_add_i32 m0, s57, 0x18000
	s_waitcnt vmcnt(2)
	s_barrier
	global_load_lds_dwordx4 v138, s[14:15]
	s_add_i32 m0, s57, 0x1a000
	v_lshl_add_u64 v[2:3], s[14:15], 0, v[142:143]
	s_add_u32 s14, s10, 0x80
	s_addc_u32 s15, s11, 0
	s_add_i32 s68, s57, 0x8000
	global_load_lds_dwordx4 v[2:3], off
	s_mov_b32 m0, s68
	s_add_i32 s69, s57, 0xa000
	global_load_lds_dwordx4 v136, s[14:15]
	v_lshl_add_u64 v[2:3], s[14:15], 0, v[140:141]
	s_add_u32 s14, s26, 0x80080
	s_mov_b32 m0, s69
	s_addc_u32 s15, s27, 0
	global_load_lds_dwordx4 v[2:3], off
	s_add_i32 m0, s57, 0x1c000
	s_nop 0
	global_load_lds_dwordx4 v138, s[14:15]
	s_add_i32 m0, s57, 0x1e000
	s_mov_b32 s12, s28
	global_load_lds_dwordx4 v142, s[14:15]
	s_mov_b32 s28, s30
	v_and_b32_e32 v1, 48, v0
	v_lshlrev_b32_e32 v2, 6, v0
	s_movk_i32 s30, 0x3c0
	v_lshlrev_b32_e32 v0, 2, v0
	v_and_or_b32 v1, v2, s30, v1
	v_and_b32_e32 v0, 32, v0
	s_waitcnt vmcnt(6)
	s_cmpk_lt_u32 s4, 0x100
	s_mov_b32 s87, 0x20000
	v_bitop3_b32 v2, v1, s7, v0 bitop3:0xde
	v_bitop3_b32 v148, s9, v1, v0 bitop3:0xf6
	s_cselect_b64 s[36:37], -1, 0
	s_add_i32 s71, 0, 0x10000
	s_add_i32 s72, 0, 0x14000
	s_brev_b32 s86, 16
	s_brev_b32 s22, 64
	s_mov_b32 s23, s87
	s_mov_b32 s14, 0x400000
	s_mov_b32 s15, s87
	s_lshl_b32 s70, s5, 6
	v_add_u32_e32 v149, s71, v148
	v_add_u32_e32 v150, s72, v148
	v_add_u32_e32 v151, 0, v2
	v_mov_b32_e32 v152, 0x7f7f7f7f
	s_mov_b32 s38, 0x3c800000
	s_mov_b32 s73, 0x200000
	s_barrier
	s_branch .LBB0_1197

; #define PG8_WAIT_V(n) asm volatile("s_waitcnt vmcnt(" #n ")" ::: "memory")
; #define PG8_BAR __builtin_amdgcn_s_barrier()
;     ...
;     const int aoff = lds_byte(wr * 64 + fr, fq * 8), boff = lds_byte(wc * 32 + fr, fq * 8);
;     ...
;         PG8_STAGE(PG8_SB(0, 0), cB, voffB); PG8_STAGE(PG8_SB(0, 1), cB + hstep, voffB); PG8_STAGE(PG8_SA(0, 0), cA, voffA); PG8_STAGE(PG8_SA(0, 1), cA + hstepA, voffA);
;         if (wr == 1) PG8_BAR;
;         PG8_WAIT_V(2); PG8_BAR;
;         PG8_STAGE(PG8_SB(1, 0), cB + kstep, voffB); PG8_STAGE(PG8_SA(1, 0), cA + kstep, voffA); PG8_STAGE(PG8_SB(1, 1), cB + hstep + kstep, voffB);
;         PG8_WAIT_V(6); PG8_BAR;
.LBB0_1364:
	s_and_b32 s0, s0, 3
	s_lshl_b32 s65, s5, 6
	s_lshl_b32 s5, s5, 13
	s_lshl_b32 s66, s0, 5
	s_lshl_b32 s7, s0, 12
	s_add_u32 s14, s82, 0x3eb00000
	s_addc_u32 s15, s83, 0
	s_add_u32 s22, s82, 0x46b00000
	s_addc_u32 s23, s83, 0
	s_add_u32 s26, s82, 0x47700000
	s_addc_u32 s27, s83, 0
	s_add_u32 s28, s12, 0x80
	s_addc_u32 s29, s13, 0
	s_add_i32 m0, s37, 0x18000
	s_waitcnt vmcnt(2)
	s_barrier
	global_load_lds_dwordx4 v138, s[28:29]
	s_add_i32 m0, s37, 0x1a000
	v_lshl_add_u64 v[2:3], s[28:29], 0, v[142:143]
	s_add_u32 s28, s10, 0x80
	s_addc_u32 s29, s11, 0
	s_add_i32 s67, s37, 0x8000
	global_load_lds_dwordx4 v[2:3], off
	s_mov_b32 m0, s67
	s_add_i32 s68, s37, 0xa000
	global_load_lds_dwordx4 v136, s[28:29]
	v_lshl_add_u64 v[2:3], s[28:29], 0, v[140:141]
	s_add_u32 s28, s12, 0x100080
	s_mov_b32 m0, s68
	s_addc_u32 s29, s13, 0
	global_load_lds_dwordx4 v[2:3], off
	s_add_i32 m0, s37, 0x1c000
	s_nop 0
	global_load_lds_dwordx4 v138, s[28:29]
	s_add_i32 m0, s37, 0x1e000
	s_cmpk_lt_u32 s4, 0x100
	global_load_lds_dwordx4 v142, s[28:29]
	v_and_b32_e32 v1, 48, v0
	v_lshlrev_b32_e32 v2, 6, v0
	s_movk_i32 s9, 0x3c0
	v_lshlrev_b32_e32 v0, 2, v0
	s_cselect_b64 s[28:29], -1, 0
	s_lshl_b32 s69, s0, 4
	v_and_or_b32 v1, v2, s9, v1
	v_and_b32_e32 v0, 32, v0
	s_waitcnt vmcnt(6)
	s_cmp_eq_u32 s0, 0
	v_bitop3_b32 v2, v1, s5, v0 bitop3:0xde
	v_bitop3_b32 v162, s7, v1, v0 bitop3:0xf6
	s_cselect_b64 s[30:31], -1, 0
	s_add_i32 s71, 0, 0x10000
	s_add_i32 s72, 0, 0x14000
	v_mov_b64_e32 v[146:147], 0x440
	v_mov_b64_e32 v[148:149], 0x43f
	s_movk_i32 s70, 0x89
	v_add_u32_e32 v163, s71, v162
	v_add_u32_e32 v164, s72, v162
	v_add_u32_e32 v165, 0, v2
	s_mov_b32 s36, 0x3c800000
	s_mov_b32 s73, 0
	s_barrier
	s_branch .LBB0_1367

; #define PG8_WAIT_V(n) asm volatile("s_waitcnt vmcnt(" #n ")" ::: "memory")
; #define PG8_BAR __builtin_amdgcn_s_barrier()
;     ...
;     const int aoff = lds_byte(wr * 64 + fr, fq * 8), boff = lds_byte(wc * 32 + fr, fq * 8);
;     ...
;         PG8_STAGE(PG8_SB(0, 0), cB, voffB); PG8_STAGE(PG8_SB(0, 1), cB + hstep, voffB); PG8_STAGE(PG8_SA(0, 0), cA, voffA); PG8_STAGE(PG8_SA(0, 1), cA + hstepA, voffA);
;         if (wr == 1) PG8_BAR;
;         PG8_WAIT_V(2); PG8_BAR;
;         PG8_STAGE(PG8_SB(1, 0), cB + kstep, voffB); PG8_STAGE(PG8_SA(1, 0), cA + kstep, voffA); PG8_STAGE(PG8_SB(1, 1), cB + hstep + kstep, voffB);
;         PG8_WAIT_V(6); PG8_BAR;
.LBB0_3416:
	s_and_b32 s12, s12, 3
	s_and_b32 s17, s58, 0xffff
	s_and_b32 s9, s35, 0xffff
	s_ashr_i32 s48, s88, 31
	s_lshl_b32 s49, s8, 6
	s_lshl_b32 s14, s8, 13
	s_lshl_b32 s20, s12, 12
	s_add_u32 s18, s28, 0x80
	s_addc_u32 s19, s29, 0
	s_add_i32 m0, s43, 0x18000
	s_waitcnt vmcnt(2)
	s_barrier
	global_load_lds_dwordx4 v128, s[18:19]
	s_add_i32 m0, s43, 0x1a000
	v_lshl_add_u64 v[2:3], s[18:19], 0, v[130:131]
	s_add_u32 s18, s30, 0x80
	s_addc_u32 s19, s31, 0
	s_add_i32 s50, s43, 0x8000
	s_add_i32 s51, s43, 0xa000
	global_load_lds_dwordx4 v[2:3], off
	s_mov_b32 m0, s50
	s_add_u32 s6, s6, 0x80
	global_load_lds_dwordx4 v128, s[18:19]
	s_mov_b32 m0, s51
	s_addc_u32 s7, s7, 0
	global_load_lds_dwordx4 v130, s[18:19]
	s_add_i32 m0, s43, 0x1c000
	s_nop 0
	global_load_lds_dwordx4 v128, s[6:7]
	s_add_i32 m0, s43, 0x1e000
	s_sext_i32_i8 s11, s4
	global_load_lds_dwordx4 v130, s[6:7]
	v_and_b32_e32 v1, 48, v0
	v_lshlrev_b32_e32 v2, 6, v0
	s_movk_i32 s4, 0x3c0
	v_lshlrev_b32_e32 v0, 2, v0
	v_and_or_b32 v1, v2, s4, v1
	v_and_b32_e32 v0, 32, v0
	s_waitcnt vmcnt(6)
	s_cmpk_lt_u32 s5, 0x100
	v_bitop3_b32 v2, v1, s14, v0 bitop3:0xde
	v_bitop3_b32 v136, s20, v1, v0 bitop3:0xf6
	s_cselect_b64 s[6:7], -1, 0
	s_add_i32 s53, 0, 0x10000
	s_add_i32 s54, 0, 0x14000
	s_mov_b32 s19, 0x20000
	s_brev_b32 s18, 8
	s_mov_b32 s8, s34
	s_lshl_b32 s52, s12, 6
	v_mov_b64_e32 v[132:133], 0x400
	v_mov_b64_e32 v[134:135], 0x3ff
	v_add_u32_e32 v137, s53, v136
	v_add_u32_e32 v138, s54, v136
	v_add_u32_e32 v139, 0, v2
	v_mov_b32_e32 v140, 0x7f7f7f7f
	s_mov_b32 s12, 0x3fb504f3
	s_mov_b32 s14, 0x3a800000
	s_barrier
	s_branch .LBB0_3419

; #define PG8_WAIT_V(n) asm volatile("s_waitcnt vmcnt(" #n ")" ::: "memory")
; #define PG8_BAR __builtin_amdgcn_s_barrier()
;     ...
;     const int aoff = lds_byte(wr * 64 + fr, fq * 8), boff = lds_byte(wc * 32 + fr, fq * 8);
;     ...
;         PG8_STAGE(PG8_SB(0, 0), cB, voffB); PG8_STAGE(PG8_SB(0, 1), cB + hstep, voffB); PG8_STAGE(PG8_SA(0, 0), cA, voffA); PG8_STAGE(PG8_SA(0, 1), cA + hstepA, voffA);
;         if (wr == 1) PG8_BAR;
;         PG8_WAIT_V(2); PG8_BAR;
;         PG8_STAGE(PG8_SB(1, 0), cB + kstep, voffB); PG8_STAGE(PG8_SA(1, 0), cA + kstep, voffA); PG8_STAGE(PG8_SB(1, 1), cB + hstep + kstep, voffB);
;         PG8_WAIT_V(6); PG8_BAR;
.LBB0_3548:
	s_lshl_b32 s7, s7, 5
	s_and_b32 s48, s7, 0x60
	s_ashr_i32 s46, s88, 31
	s_lshl_b32 s47, s10, 6
	s_lshl_b32 s12, s10, 13
	s_lshl_b32 s13, s48, 7
	s_add_u32 s10, s26, 0x80
	s_addc_u32 s11, s27, 0
	s_add_i32 m0, s23, 0x18000
	s_waitcnt vmcnt(2)
	s_barrier
	global_load_lds_dwordx4 v128, s[10:11]
	s_add_i32 m0, s23, 0x1a000
	v_lshl_add_u64 v[2:3], s[10:11], 0, v[130:131]
	s_add_u32 s10, s24, 0x80
	s_addc_u32 s11, s25, 0
	s_add_i32 s49, s23, 0x8000
	global_load_lds_dwordx4 v[2:3], off
	s_mov_b32 m0, s49
	s_add_i32 s50, s23, 0xa000
	global_load_lds_dwordx4 v134, s[10:11]
	v_lshl_add_u64 v[2:3], s[10:11], 0, v[132:133]
	s_add_u32 s10, s26, 0x100080
	s_mov_b32 m0, s50
	s_addc_u32 s11, s27, 0
	global_load_lds_dwordx4 v[2:3], off
	s_add_i32 m0, s23, 0x1c000
	s_nop 0
	global_load_lds_dwordx4 v128, s[10:11]
	s_add_i32 m0, s23, 0x1e000
	s_sext_i32_i16 s53, s4
	global_load_lds_dwordx4 v130, s[10:11]
	v_and_b32_e32 v1, 48, v0
	v_lshlrev_b32_e32 v2, 6, v0
	s_movk_i32 s4, 0x3c0
	v_lshlrev_b32_e32 v0, 2, v0
	s_mov_b32 s7, 0
	v_and_or_b32 v1, v2, s4, v1
	v_and_b32_e32 v0, 32, v0
	s_waitcnt vmcnt(6)
	s_cmpk_lt_u32 s5, 0x100
	v_bitop3_b32 v2, v1, s12, v0 bitop3:0xde
	v_bitop3_b32 v140, s13, v1, v0 bitop3:0xf6
	s_cselect_b64 s[10:11], -1, 0
	v_mov_b64_e32 v[136:137], s[6:7]
	s_add_i32 s6, 0, 0x10000
	s_add_i32 s51, 0, 0x14000
	v_add_u32_e32 v141, s6, v140
	v_add_u32_e32 v142, s51, v140
	v_add_u32_e32 v143, 0, v2
	s_movk_i32 s52, 0x2b00
	s_barrier
	s_branch .LBB0_3551

; #define PG8_WAIT_V(n) asm volatile("s_waitcnt vmcnt(" #n ")" ::: "memory")
; #define PG8_WAIT_L(n) asm volatile("s_waitcnt lgkmcnt(" #n ")" ::: "memory")
; #define PG8_BAR __builtin_amdgcn_s_barrier()
; #define PG8_SCHED __builtin_amdgcn_sched_barrier(0)
;     ...
;     Unit cur, nxt; int ui = 0;
;     if (!S.next(0, cur)) return;
;     f32x4 acc[2][2][4][2];
; #pragma unroll
;     for (int a = 0; a < 2; ++a)
; #pragma unroll
;         for (int b = 0; b < 2; ++b)
; #pragma unroll
;             for (int m = 0; m < 4; ++m)
; #pragma unroll
;                 for (int n = 0; n < 2; ++n) acc[a][b][m][n] = (f32x4){0.f, 0.f, 0.f, 0.f};
;     bf16x8 At[4][2], B0[2][2], B1[2][2]; i32x8_t At8[4], B08[2], B18[2];
;     const char* cA = (const char*)g.A + (size_t)cur.pm * tstepA; const char* cB = (const char*)g.Bt + (size_t)cur.pn * tstep;
;     S.a_ready(cur);
;     if constexpr (SP2) {
;         PG8_STAGE(PG8_SB(0, 0), cB, voffB); PG8_STAGE(PG8_SB(0, 1), cB + hstep, voffB); PG8_STAGE(PG8_SA(0, 0), cA, voffA); PG8_STAGE(PG8_SA(0, 1), cA + hstepA, voffA);
;         if (wr == 1) PG8_BAR;
;         PG8_WAIT_V(2); PG8_BAR;
;         PG8_STAGE(PG8_SB(1, 0), cB + kstep, voffB); PG8_STAGE(PG8_SA(1, 0), cA + kstep, voffA); PG8_STAGE(PG8_SB(1, 1), cB + hstep + kstep, voffB);
;         PG8_WAIT_V(6); PG8_BAR;
;     ...
;             PG8_LDB(B0, 0, 0); PG8_LDB(B1, 0, 1); PG8_SCHED; PG8_LDA(At, 0, 0); PG8_STAGE(PG8_SA(1, 1), a1 + hstepA, voffA);
;             PG8_WAIT_V(8); PG8_WAIT_L(0); PG8_BAR; PG8_MMA(0, 0, At, B0); PG8_MMA(0, 1, At, B1); PG8_BAR; PG8_SCHED;
.LBB0_3565:
	v_and_b32_e32 v2, 48, v1
	v_lshlrev_b32_e32 v3, 6, v1
	s_movk_i32 s18, 0x3c0
	s_lshl_b32 s6, s6, 5
	v_and_or_b32 v2, v3, s18, v2
	s_and_b32 s18, s6, 0x60
	s_lshl_b32 s15, s7, 6
	s_lshl_b32 s7, s7, 13
	s_lshl_b32 s6, s18, 7
	v_lshlrev_b32_e32 v1, 2, v1
	s_add_u32 s20, s4, 0x80
	v_and_b32_e32 v1, 32, v1
	s_addc_u32 s21, s5, 0
	v_bitop3_b32 v4, v2, s7, v1 bitop3:0xde
	v_bitop3_b32 v5, s6, v2, v1 bitop3:0xf6
	s_add_i32 m0, s3, 0x18000
	s_waitcnt vmcnt(2)
	s_barrier
	s_mov_b64 s[6:7], 0x80
	global_load_lds_dwordx4 v64, s[20:21]
	s_add_i32 m0, s3, 0x1a000
	s_add_i32 s19, s3, 0x8000
	global_load_lds_dwordx4 v66, s[20:21]
	v_lshl_add_u64 v[2:3], v[74:75], 0, s[6:7]
	s_mov_b32 m0, s19
	v_readfirstlane_b32 s21, v3
	v_readfirstlane_b32 s20, v2
	v_add_u32_e32 v0, s11, v0
	v_ashrrev_i32_e32 v1, 31, v0
	s_nop 2
	global_load_lds_dwordx4 v70, s[20:21]
	v_lshl_add_u64 v[2:3], s[20:21], 0, v[68:69]
	s_add_i32 s20, s3, 0xa000
	s_add_u32 s22, s4, 0x100080
	s_mov_b32 m0, s20
	s_addc_u32 s23, s5, 0
	global_load_lds_dwordx4 v[2:3], off
	s_add_i32 m0, s3, 0x1c000
	s_nop 0
	global_load_lds_dwordx4 v64, s[22:23]
	s_add_i32 m0, s3, 0x1e000
	s_add_u32 s8, s82, s8
	global_load_lds_dwordx4 v66, s[22:23]
	v_lshlrev_b64 v[0:1], 20, v[0:1]
	s_addc_u32 s9, s83, s9
	v_lshl_add_u64 v[0:1], s[82:83], 0, v[0:1]
	s_mov_b64 s[22:23], 0x1ab00000
	s_add_u32 s21, s8, 0x7b00100
	s_waitcnt vmcnt(6)
	v_lshl_add_u64 v[76:77], v[0:1], 0, s[22:23]
	s_addc_u32 s22, s9, 0
	s_add_i32 s26, 0, 0x10000
	s_add_i32 s28, 0, 0x14000
	s_add_i32 s30, 0, 0x18000
	s_add_i32 s33, 0, 0x1c000
	v_mov_b32_e32 v0, 0
	v_add_u32_e32 v73, s26, v5
	v_add_u32_e32 v80, s28, v5
	s_add_i32 s26, s26, s10
	s_add_i32 s28, s28, s10
	v_add_u32_e32 v82, s30, v5
	v_add_u32_e32 v83, s33, v5
	s_add_i32 s30, s30, s10
	s_add_i32 s33, s33, s10
	s_mov_b32 s23, -2
	s_mov_b64 s[8:9], 0x100
	v_add_u32_e32 v81, 0, v4
	s_add_i32 s24, s3, 0xc000
	s_add_i32 s25, s3, 0xe000
	s_add_i32 s27, s26, 0x2000
	s_add_i32 s29, s28, 0x2000
	s_add_i32 s31, s30, 0x2000
	s_add_i32 s36, s33, 0x2000
	v_mov_b32_e32 v1, v0
	v_mov_b32_e32 v2, v0
	v_mov_b32_e32 v3, v0
	v_mov_b32_e32 v4, v0
	v_mov_b32_e32 v5, v0
	v_mov_b32_e32 v6, v0
	v_mov_b32_e32 v7, v0
	v_mov_b32_e32 v16, v0
	v_mov_b32_e32 v17, v0
	v_mov_b32_e32 v18, v0
	v_mov_b32_e32 v19, v0
	v_mov_b32_e32 v20, v0
	v_mov_b32_e32 v21, v0
	v_mov_b32_e32 v22, v0
	v_mov_b32_e32 v23, v0
	v_mov_b32_e32 v32, v0
	v_mov_b32_e32 v33, v0
	v_mov_b32_e32 v34, v0
	v_mov_b32_e32 v35, v0
	v_mov_b32_e32 v36, v0
	v_mov_b32_e32 v37, v0
	v_mov_b32_e32 v38, v0
	v_mov_b32_e32 v39, v0
	v_mov_b32_e32 v48, v0
	v_mov_b32_e32 v49, v0
	v_mov_b32_e32 v50, v0
	v_mov_b32_e32 v51, v0
	v_mov_b32_e32 v52, v0
	v_mov_b32_e32 v53, v0
	v_mov_b32_e32 v54, v0
	v_mov_b32_e32 v55, v0
	v_mov_b32_e32 v8, v0
	v_mov_b32_e32 v9, v0
	v_mov_b32_e32 v10, v0
	v_mov_b32_e32 v11, v0
	v_mov_b32_e32 v12, v0
	v_mov_b32_e32 v13, v0
	v_mov_b32_e32 v14, v0
	v_mov_b32_e32 v15, v0
	v_mov_b32_e32 v24, v0
	v_mov_b32_e32 v25, v0
	v_mov_b32_e32 v26, v0
	v_mov_b32_e32 v27, v0
	v_mov_b32_e32 v28, v0
	v_mov_b32_e32 v29, v0
	v_mov_b32_e32 v30, v0
	v_mov_b32_e32 v31, v0
	v_mov_b32_e32 v40, v0
	v_mov_b32_e32 v41, v0
	v_mov_b32_e32 v42, v0
	v_mov_b32_e32 v43, v0
	v_mov_b32_e32 v44, v0
	v_mov_b32_e32 v45, v0
	v_mov_b32_e32 v46, v0
	v_mov_b32_e32 v47, v0
	v_mov_b32_e32 v56, v0
	v_mov_b32_e32 v57, v0
	v_mov_b32_e32 v58, v0
	v_mov_b32_e32 v59, v0
	v_mov_b32_e32 v60, v0
	v_mov_b32_e32 v61, v0
	v_mov_b32_e32 v62, v0
	v_mov_b32_e32 v63, v0
	s_barrier
.LBB0_3566:
	ds_read_b128 v[84:87], v73
	ds_read_b128 v[88:91], v73 offset:1024
	ds_read_b128 v[92:95], v73 offset:2048
	ds_read_b128 v[96:99], v73 offset:3072
	ds_read_b128 v[100:103], v80
	ds_read_b128 v[104:107], v80 offset:1024
	ds_read_b128 v[108:111], v80 offset:2048
	ds_read_b128 v[112:115], v80 offset:3072
	s_cmp_eq_u32 s23, 60
	v_lshl_add_u64 v[78:79], v[76:77], 0, s[8:9]
	s_cselect_b64 vcc, -1, 0
	v_cndmask_b32_e32 v149, v79, v75, vcc
	v_cndmask_b32_e32 v148, v78, v74, vcc
	v_lshl_add_u64 v[76:77], v[76:77], 0, s[6:7]
	s_cselect_b32 s10, s4, s21
	s_cselect_b32 s11, s5, s22
	v_lshl_add_u64 v[150:151], v[148:149], 0, s[6:7]
	v_readfirstlane_b32 s39, v77
	v_readfirstlane_b32 s38, v76
	s_mov_b32 m0, s24
	ds_read_b128 v[116:119], v81
	ds_read_b128 v[120:123], v81 offset:1024
	ds_read_b128 v[124:127], v81 offset:2048
	ds_read_b128 v[128:131], v81 offset:3072
	ds_read_b128 v[132:135], v81 offset:4096
	ds_read_b128 v[136:139], v81 offset:5120
	ds_read_b128 v[140:143], v81 offset:6144
	ds_read_b128 v[144:147], v81 offset:7168
	global_load_lds_dwordx4 v70, s[38:39]
	s_mov_b32 m0, s25
	s_nop 0
	global_load_lds_dwordx4 v68, s[38:39]
	s_waitcnt vmcnt(8)
	s_waitcnt lgkmcnt(0)
	s_barrier
; #define PG8_WAIT_V(n) asm volatile("s_waitcnt vmcnt(" #n ")" ::: "memory")
; #define PG8_WAIT_L(n) asm volatile("s_waitcnt lgkmcnt(" #n ")" ::: "memory")
; #define PG8_BAR __builtin_amdgcn_s_barrier()
; #define PG8_SCHED __builtin_amdgcn_sched_barrier(0)
;     ...
;             PG8_WAIT_V(8); PG8_WAIT_L(0); PG8_BAR; PG8_MMA(0, 0, At, B0); PG8_MMA(0, 1, At, B1); PG8_BAR; PG8_SCHED;
;             if constexpr (!HALFU) PG8_LDA(At, 0, 1); PG8_STAGE(PG8_SB(0, 0), b2, voffB); PG8_STAGE(PG8_SB(0, 1), b2 + hstep, voffB); PG8_STAGE(PG8_SA(0, 0), a2, voffA);
;             PG8_WAIT_V(8); PG8_WAIT_L(0); PG8_BAR; if constexpr (!HALFU) { PG8_MMA(1, 0, At, B0); PG8_MMA(1, 1, At, B1); } PG8_BAR; PG8_SCHED;
;             PG8_LDB(B0, 1, 0); PG8_LDB(B1, 1, 1); PG8_SCHED; PG8_LDA(At, 1, 0); PG8_STAGE(PG8_SA(0, 1), a2 + hstepA, voffA);
;             PG8_WAIT_V(8); PG8_WAIT_L(0); PG8_BAR; PG8_MMA(0, 0, At, B0); PG8_MMA(0, 1, At, B1); PG8_BAR; PG8_SCHED;
;             if constexpr (!HALFU) PG8_LDA(At, 1, 1); PG8_STAGE(PG8_SB(1, 0), b3, voffB); PG8_STAGE(PG8_SB(1, 1), b3 + hstep, voffB); PG8_STAGE(PG8_SA(1, 0), a3, voffA);
;             PG8_WAIT_V(8); PG8_WAIT_L(0); PG8_BAR; if constexpr (!HALFU) { PG8_MMA(1, 0, At, B0); PG8_MMA(1, 1, At, B1); } PG8_BAR; PG8_SCHED;
	s_setprio 1
	s_waitcnt lgkmcnt(0)
	v_mfma_f32_16x16x32_bf16 v[60:63], v[84:87], v[116:119], v[60:63]
	v_mfma_f32_16x16x32_bf16 v[56:59], v[92:95], v[116:119], v[56:59]
	v_mfma_f32_16x16x32_bf16 v[44:47], v[84:87], v[124:127], v[44:47]
	v_mfma_f32_16x16x32_bf16 v[40:43], v[92:95], v[124:127], v[40:43]
	v_mfma_f32_16x16x32_bf16 v[28:31], v[84:87], v[132:135], v[28:31]
	v_mfma_f32_16x16x32_bf16 v[24:27], v[92:95], v[132:135], v[24:27]
	v_mfma_f32_16x16x32_bf16 v[12:15], v[84:87], v[140:143], v[12:15]
	v_mfma_f32_16x16x32_bf16 v[8:11], v[92:95], v[140:143], v[8:11]
	v_mfma_f32_16x16x32_bf16 v[60:63], v[88:91], v[120:123], v[60:63]
	v_mfma_f32_16x16x32_bf16 v[56:59], v[96:99], v[120:123], v[56:59]
	v_mfma_f32_16x16x32_bf16 v[44:47], v[88:91], v[128:131], v[44:47]
	v_mfma_f32_16x16x32_bf16 v[40:43], v[96:99], v[128:131], v[40:43]
	v_mfma_f32_16x16x32_bf16 v[28:31], v[88:91], v[136:139], v[28:31]
	v_mfma_f32_16x16x32_bf16 v[24:27], v[96:99], v[136:139], v[24:27]
	v_mfma_f32_16x16x32_bf16 v[12:15], v[88:91], v[144:147], v[12:15]
	v_mfma_f32_16x16x32_bf16 v[8:11], v[96:99], v[144:147], v[8:11]
	s_setprio 0
	s_setprio 1
	v_mfma_f32_16x16x32_bf16 v[52:55], v[100:103], v[116:119], v[52:55]
	v_mfma_f32_16x16x32_bf16 v[48:51], v[108:111], v[116:119], v[48:51]
	v_mfma_f32_16x16x32_bf16 v[36:39], v[100:103], v[124:127], v[36:39]
	v_mfma_f32_16x16x32_bf16 v[32:35], v[108:111], v[124:127], v[32:35]
	v_mfma_f32_16x16x32_bf16 v[20:23], v[100:103], v[132:135], v[20:23]
	v_mfma_f32_16x16x32_bf16 v[16:19], v[108:111], v[132:135], v[16:19]
	v_mfma_f32_16x16x32_bf16 v[4:7], v[100:103], v[140:143], v[4:7]
	v_mfma_f32_16x16x32_bf16 v[0:3], v[108:111], v[140:143], v[0:3]
	v_mfma_f32_16x16x32_bf16 v[52:55], v[104:107], v[120:123], v[52:55]
	v_mfma_f32_16x16x32_bf16 v[48:51], v[112:115], v[120:123], v[48:51]
	v_mfma_f32_16x16x32_bf16 v[36:39], v[104:107], v[128:131], v[36:39]
	v_mfma_f32_16x16x32_bf16 v[32:35], v[112:115], v[128:131], v[32:35]
	v_mfma_f32_16x16x32_bf16 v[20:23], v[104:107], v[136:139], v[20:23]
	v_mfma_f32_16x16x32_bf16 v[16:19], v[112:115], v[136:139], v[16:19]
	v_mfma_f32_16x16x32_bf16 v[4:7], v[104:107], v[144:147], v[4:7]
	v_mfma_f32_16x16x32_bf16 v[0:3], v[112:115], v[144:147], v[0:3]
	s_setprio 0
	s_barrier
	s_mov_b32 m0, s26
	s_add_u32 s38, s10, 0x100000
	global_load_lds_dwordx4 v64, s[10:11]
	s_mov_b32 m0, s27
	s_addc_u32 s39, s11, 0
	global_load_lds_dwordx4 v66, s[10:11]
	s_mov_b32 m0, s28
	s_nop 0
	global_load_lds_dwordx4 v64, s[38:39]
	v_lshl_add_u64 v[76:77], s[38:39], 0, v[66:67]
	s_mov_b32 m0, s29
	v_readfirstlane_b32 s39, v149
	v_readfirstlane_b32 s38, v148
	global_load_lds_dwordx4 v[76:77], off
	s_nop 0
	s_mov_b32 m0, s3
	s_nop 1
	global_load_lds_dwordx4 v70, s[38:39]
	s_mov_b32 m0, s13
	s_nop 0
	global_load_lds_dwordx4 v68, s[38:39]
	s_waitcnt vmcnt(8)
	s_waitcnt lgkmcnt(0)
	s_barrier
	s_barrier
	ds_read_b128 v[84:87], v82
	ds_read_b128 v[88:91], v82 offset:1024
	ds_read_b128 v[92:95], v82 offset:2048
	ds_read_b128 v[96:99], v82 offset:3072
	ds_read_b128 v[100:103], v83
	ds_read_b128 v[104:107], v83 offset:1024
	ds_read_b128 v[108:111], v83 offset:2048
	ds_read_b128 v[112:115], v83 offset:3072
	s_mov_b32 m0, s14
	ds_read_b128 v[116:119], v81 offset:32768
	ds_read_b128 v[120:123], v81 offset:33792
	ds_read_b128 v[124:127], v81 offset:34816
	ds_read_b128 v[128:131], v81 offset:35840
	ds_read_b128 v[132:135], v81 offset:36864
	ds_read_b128 v[136:139], v81 offset:37888
	ds_read_b128 v[140:143], v81 offset:38912
	ds_read_b128 v[144:147], v81 offset:39936
	global_load_lds_dwordx4 v70, s[38:39]
	s_mov_b32 m0, s17
	s_nop 0
	global_load_lds_dwordx4 v68, s[38:39]
	s_waitcnt vmcnt(8)
	s_waitcnt lgkmcnt(0)
	s_barrier
	s_setprio 1
	s_waitcnt lgkmcnt(0)
	v_mfma_f32_16x16x32_bf16 v[60:63], v[84:87], v[116:119], v[60:63]
	v_mfma_f32_16x16x32_bf16 v[56:59], v[92:95], v[116:119], v[56:59]
	v_mfma_f32_16x16x32_bf16 v[44:47], v[84:87], v[124:127], v[44:47]
	v_mfma_f32_16x16x32_bf16 v[40:43], v[92:95], v[124:127], v[40:43]
	v_mfma_f32_16x16x32_bf16 v[28:31], v[84:87], v[132:135], v[28:31]
	v_mfma_f32_16x16x32_bf16 v[24:27], v[92:95], v[132:135], v[24:27]
	v_mfma_f32_16x16x32_bf16 v[12:15], v[84:87], v[140:143], v[12:15]
	v_mfma_f32_16x16x32_bf16 v[8:11], v[92:95], v[140:143], v[8:11]
	v_mfma_f32_16x16x32_bf16 v[60:63], v[88:91], v[120:123], v[60:63]
	v_mfma_f32_16x16x32_bf16 v[56:59], v[96:99], v[120:123], v[56:59]
	v_mfma_f32_16x16x32_bf16 v[44:47], v[88:91], v[128:131], v[44:47]
	v_mfma_f32_16x16x32_bf16 v[40:43], v[96:99], v[128:131], v[40:43]
	v_mfma_f32_16x16x32_bf16 v[28:31], v[88:91], v[136:139], v[28:31]
	v_mfma_f32_16x16x32_bf16 v[24:27], v[96:99], v[136:139], v[24:27]
	v_mfma_f32_16x16x32_bf16 v[12:15], v[88:91], v[144:147], v[12:15]
	v_mfma_f32_16x16x32_bf16 v[8:11], v[96:99], v[144:147], v[8:11]
	s_setprio 0
	s_setprio 1
	v_mfma_f32_16x16x32_bf16 v[52:55], v[100:103], v[116:119], v[52:55]
	s_add_u32 s38, s10, 0x80
	s_addc_u32 s39, s11, 0
	v_mfma_f32_16x16x32_bf16 v[48:51], v[108:111], v[116:119], v[48:51]
	v_mfma_f32_16x16x32_bf16 v[36:39], v[100:103], v[124:127], v[36:39]
	v_mfma_f32_16x16x32_bf16 v[32:35], v[108:111], v[124:127], v[32:35]
	v_mfma_f32_16x16x32_bf16 v[20:23], v[100:103], v[132:135], v[20:23]
	v_mfma_f32_16x16x32_bf16 v[16:19], v[108:111], v[132:135], v[16:19]
	v_mfma_f32_16x16x32_bf16 v[4:7], v[100:103], v[140:143], v[4:7]
	v_mfma_f32_16x16x32_bf16 v[0:3], v[108:111], v[140:143], v[0:3]
	v_mfma_f32_16x16x32_bf16 v[52:55], v[104:107], v[120:123], v[52:55]
	v_mfma_f32_16x16x32_bf16 v[48:51], v[112:115], v[120:123], v[48:51]
	v_mfma_f32_16x16x32_bf16 v[36:39], v[104:107], v[128:131], v[36:39]
	v_mfma_f32_16x16x32_bf16 v[32:35], v[112:115], v[128:131], v[32:35]
	v_mfma_f32_16x16x32_bf16 v[20:23], v[104:107], v[136:139], v[20:23]
	v_mfma_f32_16x16x32_bf16 v[16:19], v[112:115], v[136:139], v[16:19]
	v_mfma_f32_16x16x32_bf16 v[4:7], v[104:107], v[144:147], v[4:7]
	v_mfma_f32_16x16x32_bf16 v[0:3], v[112:115], v[144:147], v[0:3]
	s_setprio 0
	s_barrier
	s_mov_b32 m0, s30
	s_add_u32 s10, s10, 0x100080
	global_load_lds_dwordx4 v64, s[38:39]
	s_mov_b32 m0, s31
	s_addc_u32 s11, s11, 0
	global_load_lds_dwordx4 v66, s[38:39]
	s_mov_b32 m0, s33
	s_nop 0
	global_load_lds_dwordx4 v64, s[10:11]
	v_lshl_add_u64 v[76:77], s[10:11], 0, v[66:67]
	s_mov_b32 m0, s36
	v_readfirstlane_b32 s11, v151
	v_readfirstlane_b32 s10, v150
	global_load_lds_dwordx4 v[76:77], off
	s_nop 0
	s_mov_b32 m0, s19
	s_nop 0
	s_nop 0
	global_load_lds_dwordx4 v70, s[10:11]
	s_mov_b32 m0, s20
	s_nop 0
	global_load_lds_dwordx4 v68, s[10:11]
	s_waitcnt vmcnt(8)
	s_waitcnt lgkmcnt(0)
	s_barrier
	s_barrier
	s_add_i32 s23, s23, 2
	s_add_u32 s21, s21, 0x100
	s_addc_u32 s22, s22, 0
	s_cmp_gt_u32 s23, 61
	v_mov_b64_e32 v[76:77], v[78:79]
	s_cbranch_scc0 .LBB0_3566
	s_cmpk_lt_u32 s12, 0x100
	s_cbranch_scc0 .LBB0_3569
	s_barrier

; #define PG8_WAIT_V(n) asm volatile("s_waitcnt vmcnt(" #n ")" ::: "memory")
; #define PG8_BAR __builtin_amdgcn_s_barrier()
;     ...
;     const int aoff = lds_byte(wr * 64 + fr, fq * 8), boff = lds_byte(wc * 32 + fr, fq * 8);
;     ...
;         PG8_STAGE(PG8_SB(0, 0), cB, voffB); PG8_STAGE(PG8_SB(0, 1), cB + hstep, voffB); PG8_STAGE(PG8_SA(0, 0), cA, voffA); PG8_STAGE(PG8_SA(0, 1), cA + hstepA, voffA);
;         if (wr == 1) PG8_BAR;
;         PG8_WAIT_V(2); PG8_BAR;
;         PG8_STAGE(PG8_SB(1, 0), cB + kstep, voffB); PG8_STAGE(PG8_SA(1, 0), cA + kstep, voffA); PG8_STAGE(PG8_SB(1, 1), cB + hstep + kstep, voffB);
;         PG8_WAIT_V(6); PG8_BAR;
.LBB0_3626:
	s_and_b32 s14, s8, 3
	s_and_b32 s17, s58, 0xffff
	s_and_b32 s9, s35, 0xffff
	s_ashr_i32 s40, s88, 31
	s_lshl_b32 s41, s7, 6
	s_lshl_b32 s7, s7, 13
	s_lshl_b32 s13, s14, 12
	s_add_u32 s18, s10, 0x80
	s_addc_u32 s19, s11, 0
	s_add_i32 m0, s33, 0x18000
	s_waitcnt vmcnt(2)
	s_barrier
	global_load_lds_dwordx4 v128, s[18:19]
	s_add_i32 m0, s33, 0x1a000
	v_lshl_add_u64 v[2:3], s[18:19], 0, v[130:131]
	s_add_u32 s18, s24, 0x80
	s_addc_u32 s19, s25, 0
	s_add_i32 s42, s33, 0x8000
	s_add_i32 s43, s33, 0xa000
	global_load_lds_dwordx4 v[2:3], off
	s_mov_b32 m0, s42
	s_add_u32 s4, s4, 0x80
	global_load_lds_dwordx4 v128, s[18:19]
	s_mov_b32 m0, s43
	s_addc_u32 s5, s5, 0
	global_load_lds_dwordx4 v130, s[18:19]
	s_add_i32 m0, s33, 0x1c000
	s_nop 0
	global_load_lds_dwordx4 v128, s[4:5]
	s_add_i32 m0, s33, 0x1e000
	v_and_b32_e32 v1, 48, v0
	global_load_lds_dwordx4 v130, s[4:5]
	v_lshlrev_b32_e32 v2, 6, v0
	s_movk_i32 s4, 0x3c0
	v_lshlrev_b32_e32 v0, 2, v0
	v_and_or_b32 v1, v2, s4, v1
	v_and_b32_e32 v0, 32, v0
	s_waitcnt vmcnt(6)
	s_cmpk_lt_u32 s6, 0x100
	s_sext_i32_i8 s50, s12
	v_bitop3_b32 v2, v1, s7, v0 bitop3:0xde
	v_bitop3_b32 v136, s13, v1, v0 bitop3:0xf6
	s_cselect_b64 s[12:13], -1, 0
	s_add_i32 s45, 0, 0x10000
	s_add_i32 s46, 0, 0x14000
	s_mov_b32 s19, 0x20000
	s_brev_b32 s18, 8
	s_mov_b32 s8, s34
	s_lshl_b32 s44, s14, 6
	v_mov_b64_e32 v[132:133], 0x400
	v_mov_b64_e32 v[134:135], 0x3ff
	v_add_u32_e32 v137, s45, v136
	v_add_u32_e32 v138, s46, v136
	v_add_u32_e32 v139, 0, v2
	v_mov_b32_e32 v140, 0x7f7f7f7f
	s_mov_b32 s14, 0x3fb504f3
	s_mov_b32 s20, 0x3a000000
	s_barrier
	s_branch .LBB0_3629
